# attn0_first_kv_tile_loads_hoisted_above_cumsum
# baseline (speedup 1.0000x reference)
.LBB0_540:
	s_and_b64 vcc, exec, s[4:5]
	s_cbranch_vccz .LBB0_513
	v_mov_b32_e32 v8, v165
	v_mov_b64_e32 v[2:3], s[18:19]
	v_readfirstlane_b32 s4, v8
	s_ashr_i32 s5, s4, 6
	s_lshl_b32 s12, s5, 5
	v_and_b32_e32 v150, 31, v8
	s_add_i32 s12, s12, s74
	v_bfe_u32 v10, v8, 5, 1
	v_or_b32_e32 v151, s12, v150
	s_movk_i32 s6, 0x600
	v_mad_i64_i32 v[2:3], s[6:7], v151, s6, v[2:3]
	v_lshlrev_b32_e32 v0, 4, v10
	v_lshl_add_u64 v[2:3], v[2:3], 0, v[0:1]
	global_load_dwordx4 v[114:117], v[2:3], off
	global_load_dwordx4 v[118:121], v[2:3], off offset:32
	global_load_dwordx4 v[122:125], v[2:3], off offset:64
	global_load_dwordx4 v[126:129], v[2:3], off offset:96
	v_ashrrev_i32_e32 v226, 3, v8
	s_or_b32 s98, s96, 1
	v_lshl_add_u32 v227, s98, 7, v226
	v_mov_b64_e32 v[228:229], s[20:21]
	s_movk_i32 s99, 0x600
	v_lshlrev_b32_e32 v230, 4, v8
	v_ashrrev_i32_e32 v232, 4, v8
	v_mad_i64_i32 v[228:229], s[100:101], v227, s99, v[228:229]
	v_and_b32_e32 v234, 0x70, v230
	v_mov_b32_e32 v235, v1
	v_lshl_add_u64 v[228:229], v[228:229], 0, v[234:235]
	s_mov_b32 s100, 0x18000
	v_ashrrev_i32_e32 v233, 31, v232
	v_add_co_u32_e32 v236, vcc, s100, v228
	v_lshlrev_b64 v[238:239], 12, v[232:233]
	s_nop 0
	v_addc_co_u32_e32 v237, vcc, 0, v229, vcc
	global_load_dwordx4 v[130:133], v[228:229], off
	global_load_dwordx4 v[134:137], v[236:237], off
	v_lshl_add_u64 v[228:229], s[22:23], 0, v[238:239]
	s_lshl_b32 s100, s98, 8
	s_mov_b32 s101, 0
	v_lshl_add_u64 v[228:229], v[228:229], 0, s[100:101]
	v_and_b32_e32 v234, 0xf0, v230
	v_lshl_add_u64 v[228:229], v[228:229], 0, v[234:235]
	s_mov_b32 s99, 0x20000
	v_add_co_u32_e32 v236, vcc, s99, v228
	s_nop 1
	v_addc_co_u32_e32 v237, vcc, 0, v229, vcc
	global_load_dwordx4 v[138:141], v[228:229], off
	global_load_dwordx4 v[142:145], v[236:237], off
	v_readlane_b32 s6, v254, 49
	v_readlane_b32 s7, v254, 50
	s_or_b64 s[2:3], s[2:3], s[6:7]
	v_and_b32_e32 v9, 63, v8
	s_and_b64 vcc, exec, s[2:3]
	s_cbranch_vccnz .LBB0_557
	s_add_i32 s2, s74, 0x100
	v_lshlrev_b32_e32 v6, 2, v8
	v_cmp_gt_i32_e32 vcc, s2, v6
	v_mov_b32_e32 v2, 0
	v_mov_b32_e32 v3, 0
	v_mov_b32_e32 v4, 0
	v_mov_b32_e32 v5, 0
	s_and_saveexec_b64 s[2:3], vcc
	s_cbranch_execz .LBB0_544
	v_readlane_b32 s6, v254, 54
	v_ashrrev_i32_e32 v7, 31, v6
	v_readlane_b32 s7, v254, 55
	s_nop 1
	v_lshl_add_u64 v[2:3], v[6:7], 2, s[6:7]
	global_load_dwordx4 v[2:5], v[2:3], off

.LBB0_557:
	v_ashrrev_i32_e32 v15, 3, v8
	s_or_b32 s5, s96, 1
	v_lshl_add_u32 v4, s5, 7, v15
	v_mov_b64_e32 v[2:3], s[20:21]
	s_movk_i32 s9, 0x600
	v_lshlrev_b32_e32 v6, 4, v8
	v_ashrrev_i32_e32 v16, 4, v8
	v_mad_i64_i32 v[2:3], s[2:3], v4, s9, v[2:3]
	v_and_b32_e32 v18, 0x70, v6
	v_mov_b32_e32 v19, v1
	v_lshl_add_u64 v[2:3], v[2:3], 0, v[18:19]
	s_mov_b32 s2, 0x18000
	v_ashrrev_i32_e32 v17, 31, v16
	v_add_co_u32_e32 v4, vcc, s2, v2
	v_lshlrev_b64 v[20:21], 12, v[16:17]
	s_nop 0
	v_addc_co_u32_e32 v5, vcc, 0, v3, vcc
	v_lshl_add_u64 v[2:3], s[22:23], 0, v[20:21]
	s_lshl_b32 s80, s5, 8
	v_lshl_add_u64 v[2:3], v[2:3], 0, s[80:81]
	v_and_b32_e32 v22, 0xf0, v6
	v_mov_b32_e32 v23, v1
	v_lshl_add_u64 v[2:3], v[2:3], 0, v[22:23]
	s_mov_b32 s2, 0x20000
	v_add_co_u32_e32 v4, vcc, s2, v2
	s_and_b32 s2, s4, 0x3fffffc0
	s_nop 0
	v_addc_co_u32_e32 v5, vcc, 0, v3, vcc
	s_lshl_b32 s3, s75, 10
	s_lshl_b32 s2, s2, 2
	s_movk_i32 s8, 0x90
	v_mov_b64_e32 v[24:25], s[26:27]
	v_and_b32_e32 v19, 7, v8
	v_mul_lo_u32 v28, v15, s8
	s_movk_i32 s8, 0x110
	s_add_i32 s3, s3, 0
	v_add_u32_e32 v15, s74, v15
	s_add_i32 s15, s2, 0
	s_or_b32 s13, s12, 31
	s_add_i32 s14, s74, 0x80
	s_lshl_b32 s7, s75, 9
	v_mul_lo_u32 v29, v16, s8
	v_lshlrev_b32_e32 v16, 4, v19
	v_add3_u32 v155, 0, v28, v18
	s_add_i32 s8, s3, 0x11a00
	v_mad_i64_i32 v[18:19], s[2:3], v15, s9, v[24:25]
	s_add_i32 s15, s15, 0x13800
	s_add_u32 s2, s7, s86
	v_mov_b32_e32 v17, v1
	v_and_b32_e32 v26, 15, v8
	s_addc_u32 s3, 0, s87
	v_mov_b32_e32 v27, v1
	v_lshlrev_b32_e32 v26, 4, v26
	v_lshl_add_u64 v[146:147], v[18:19], 0, v[16:17]
	v_lshl_add_u64 v[16:17], s[2:3], 0, v[20:21]
	v_lshlrev_b32_e32 v23, 3, v10
	v_lshl_add_u64 v[148:149], v[16:17], 0, v[26:27]
	v_mov_b32_e32 v16, v1
	v_mov_b32_e32 v17, v1
	v_lshlrev_b32_e32 v152, 2, v10
	v_cmp_gt_u32_e64 s[4:5], 32, v9
	v_mov_b32_e32 v2, v1
	v_mov_b32_e32 v3, v1
	v_mov_b32_e32 v4, v1
	v_mov_b32_e32 v5, v1
	v_mov_b32_e32 v6, v1
	v_mov_b32_e32 v7, v1
	v_mov_b32_e32 v8, v1
	v_mov_b32_e32 v9, v1
	v_mov_b32_e32 v10, v1
	v_mov_b32_e32 v11, v1
	v_mov_b32_e32 v12, v1
	v_mov_b32_e32 v13, v1
	v_mov_b32_e32 v14, v1
	v_add3_u32 v156, 0, v29, v22
	v_mov_b32_e32 v15, v1
	v_lshlrev_b32_e32 v168, 1, v23
	v_mov_b64_e32 v[32:33], v[16:17]
	v_mov_b64_e32 v[48:49], v[16:17]
	s_mov_b32 s6, 0
	v_mul_u32_u24_e32 v153, 0x90, v150
	v_mul_u32_u24_e32 v154, 0x110, v150
	v_add_u32_e32 v157, s8, v0
	v_lshl_add_u32 v166, v150, 2, s15
	s_mov_b64 s[8:9], 0
	v_mov_b32_e32 v167, 0
	v_mov_b64_e32 v[30:31], v[14:15]
	v_mov_b64_e32 v[28:29], v[12:13]
	v_mov_b64_e32 v[26:27], v[10:11]
	v_mov_b64_e32 v[24:25], v[8:9]
	v_mov_b64_e32 v[22:23], v[6:7]
	v_mov_b64_e32 v[20:21], v[4:5]
	v_mov_b64_e32 v[18:19], v[2:3]
	v_mov_b64_e32 v[46:47], v[14:15]
	v_mov_b64_e32 v[44:45], v[12:13]
	v_mov_b64_e32 v[42:43], v[10:11]
	v_mov_b64_e32 v[40:41], v[8:9]
	v_mov_b64_e32 v[38:39], v[6:7]
	v_mov_b64_e32 v[36:37], v[4:5]
	v_mov_b64_e32 v[34:35], v[2:3]
	s_waitcnt vmcnt(3)
	ds_write_b128 v155, v[130:133]
	s_waitcnt vmcnt(2)
	ds_write_b128 v155, v[134:137] offset:9216
	s_waitcnt vmcnt(1)
	ds_write_b128 v156, v[138:141] offset:36864
	s_waitcnt vmcnt(0)
	ds_write_b128 v156, v[142:145] offset:45568
	s_waitcnt lgkmcnt(0)
	s_barrier
